# scan phase tail: thread-to-column mapping changed so a quad reads and writes 64 contiguous bytes per instruction (address constants only)
# speedup vs baseline: 1.0233x; 1.0114x over previous
.LBB0_421:
	s_lshl_b32 s2, s50, 8
	v_and_b32_e32 v3, 31, v85
	s_and_b32 s33, s2, 0xfffff000
	s_lshl_b32 s2, s51, 9
	s_add_i32 s52, s33, s2
	s_movk_i32 s2, 0x80
	v_lshlrev_b32_e32 v9, 2, v84
	v_lshl_or_b32 v164, v8, 5, v3
	v_lshlrev_b32_e32 v8, 7, v8
	v_lshlrev_b32_e32 v11, 3, v85
	v_cmp_gt_u32_e32 vcc, s2, v86
	v_add_u32_e32 v167, s54, v9
	v_mul_lo_u32 v10, v164, s61
	v_add_u32_e32 v172, s56, v9
	v_add3_u32 v8, s91, v8, v9
	v_ashrrev_i32_e32 v9, 2, v86
	s_movk_i32 s2, 0x210
	v_and_b32_e32 v11, 0x18, v11
	v_add_u32_e32 v171, s91, v10
	v_mul_lo_u32 v10, v9, s2
	v_lshlrev_b32_e32 v12, 2, v11
	v_add3_u32 v173, s91, v10, v12
	v_and_b32_e32 v12, 64, v160
	v_xor_b32_e32 v10, 1, v160
	v_add_u32_e32 v12, 64, v12
	v_cmp_lt_i32_e64 s[2:3], v10, v12
	v_and_b32_e32 v4, 0x7f, v86
	v_lshlrev_b32_e32 v5, 2, v4
	v_cndmask_b32_e64 v10, v160, v10, s[2:3]
	v_lshlrev_b32_e32 v174, 2, v10
	v_xor_b32_e32 v10, 2, v160
	v_readlane_b32 s36, v254, 15
	v_add_u32_e32 v166, s55, v5
	v_cmp_lt_i32_e64 s[2:3], v10, v12
	v_add_u32_e32 v176, s56, v5
	v_add_u32_e32 v177, s54, v5
	v_or_b32_e32 v5, 27, v84
	v_readlane_b32 s37, v254, 16
	s_and_b32 s4, s50, 15
	v_cndmask_b32_e64 v10, v160, v10, s[2:3]
	v_cmp_gt_u32_e64 s[2:3], v5, v3
	v_or_b32_e32 v5, 26, v84
	s_load_dwordx2 s[36:37], s[36:37], 0x58
	s_mul_i32 s53, s4, 0x4080
	v_lshlrev_b32_e32 v175, 2, v10
	v_lshl_or_b32 v10, s4, 7, v11
	v_cmp_gt_u32_e64 s[4:5], v5, v3
	v_or_b32_e32 v5, 25, v84
	v_lshlrev_b32_e32 v112, 1, v11
	v_cmp_gt_u32_e64 s[6:7], v5, v3
	v_or_b32_e32 v5, 24, v84
	v_lshl_add_u64 v[150:151], s[38:39], 0, v[112:113]
	v_lshlrev_b32_e32 v112, 1, v10
	v_cmp_gt_u32_e64 s[8:9], v5, v3
	v_or_b32_e32 v5, 19, v84
	v_lshl_add_u64 v[152:153], s[44:45], 0, v[112:113]
	v_cmp_gt_u32_e64 s[10:11], v5, v3
	v_or_b32_e32 v5, 18, v84
	v_lshlrev_b32_e32 v112, 2, v10
	v_cmp_gt_u32_e64 s[12:13], v5, v3
	v_or_b32_e32 v5, 17, v84
	s_waitcnt lgkmcnt(0)
	v_lshl_add_u64 v[154:155], s[36:37], 0, v[112:113]
	s_lshl_b32 s36, s85, 9
	v_cmp_gt_u32_e64 s[14:15], v5, v3
	v_or_b32_e32 v5, 16, v84
	s_add_i32 s36, s36, s33
	v_cmp_gt_u32_e64 s[16:17], v5, v3
	v_or_b32_e32 v5, 11, v84
	v_add_u32_e32 v9, s36, v9
	s_lshl_b32 s33, s50, 12
	v_ashrrev_i32_e32 v2, 7, v86
	s_add_i32 s46, s53, 0xc1800
	v_cmp_gt_u32_e64 s[18:19], v5, v3
	v_or_b32_e32 v5, 10, v84
	v_subrev_u32_e32 v156, s33, v9
	s_ashr_i32 s33, s52, 31
	v_lshlrev_b32_e32 v0, 5, v2
	v_cmp_gt_u32_e64 s[20:21], v5, v3
	v_or_b32_e32 v5, 9, v84
	s_add_u32 s36, s52, s53
	v_ashrrev_i32_e32 v1, 31, v0
	v_cmp_gt_u32_e64 s[22:23], v5, v3
	v_or_b32_e32 v5, 8, v84
	s_addc_u32 s37, s33, 0
	v_mov_b32_e32 v7, s91
	v_cmp_gt_u32_e64 s[24:25], v5, v3
	v_or_b32_e32 v5, 3, v84
	v_lshl_add_u64 v[0:1], s[36:37], 0, v[0:1]
	v_lshlrev_b32_e32 v6, 1, v4
	v_mad_u32_u24 v4, v4, s61, v7
	v_lshlrev_b32_e32 v7, 6, v2
	v_lshlrev_b32_e32 v168, 3, v163
	v_lshlrev_b32_e32 v169, 4, v163
	v_cmp_gt_u32_e64 s[26:27], v5, v3
	v_or_b32_e32 v5, 2, v84
	v_mul_lo_u32 v2, v2, s62
	v_lshlrev_b64 v[0:1], 8, v[0:1]
	v_add_u32_e32 v170, s91, v169
	v_cmp_gt_u32_e64 s[28:29], v5, v3
	v_cmp_lt_u32_e64 s[30:31], v84, v3
	v_cmp_gt_u32_e64 s[34:35], v84, v3
	v_add3_u32 v178, s91, v6, v2
	v_mul_u32_u24_e32 v179, 0x110, v3
	v_add_u32_e32 v2, s91, v168
	v_mul_u32_u24_e32 v5, 0x90, v3
	v_mul_u32_u24_e32 v3, 0x210, v3
	v_or_b32_e32 v0, v0, v6
	v_lshl_add_u32 v165, v86, 2, s55
	v_lshl_add_u64 v[158:159], s[0:1], 0, v[0:1]
	s_mov_b64 s[52:53], 0
	v_add_u32_e32 v112, v4, v7
	v_add_u32_e32 v180, v2, v179
	v_add_u32_e32 v181, v170, v5
	v_add_u32_e32 v182, v8, v3
	s_branch .LBB0_423
.LBB0_422:
	s_or_b64 exec, exec, s[36:37]
	s_waitcnt lgkmcnt(0)
	s_barrier
	v_mov_b32_e32 v232, v156
	v_ashrrev_i32_e32 v233, 31, v156
	v_lshl_add_u64 v[232:233], v[232:233], 0, s[46:47]
	v_lshlrev_b64 v[232:233], 8, v[232:233]
	v_lshl_add_u64 v[232:233], v[150:151], 0, v[232:233]
	global_load_dwordx4 v[216:219], v[232:233], off offset:192
	global_load_dwordx4 v[220:223], v[232:233], off offset:128
	global_load_dwordx4 v[224:227], v[232:233], off offset:64
	global_load_dwordx4 v[228:231], v[232:233], off
	ds_read_b128 v[0:3], v167
	ds_read_b128 v[4:7], v167 offset:416
	ds_read_b128 v[8:11], v167 offset:448
	v_add_u32_e32 v157, v170, v179
	s_add_u32 s52, s52, 0x4000
	s_waitcnt lgkmcnt(2)
	v_pk_mul_f32 v[48:49], v[108:109], v[0:1]
	v_pk_mul_f32 v[50:51], v[114:115], v[2:3]
	ds_read_b128 v[0:3], v167 offset:32
	ds_read_b128 v[12:15], v167 offset:480
	v_cvt_pk_bf16_f32 v64, v48, v49
	v_cvt_pk_bf16_f32 v65, v50, v51
	s_waitcnt lgkmcnt(3)
	v_pk_mul_f32 v[4:5], v[144:145], v[4:5]
	s_waitcnt lgkmcnt(1)
	v_pk_mul_f32 v[52:53], v[52:53], v[0:1]
	v_pk_mul_f32 v[54:55], v[54:55], v[2:3]
	ds_read_b128 v[0:3], v167 offset:64
	v_cvt_pk_bf16_f32 v66, v52, v53
	v_cvt_pk_bf16_f32 v67, v54, v55
	v_pk_mul_f32 v[6:7], v[138:139], v[6:7]
	v_pk_mul_f32 v[8:9], v[146:147], v[8:9]
	s_waitcnt lgkmcnt(0)
	v_pk_mul_f32 v[56:57], v[56:57], v[0:1]
	v_pk_mul_f32 v[58:59], v[58:59], v[2:3]
	ds_read_b128 v[0:3], v167 offset:96
	v_pk_mul_f32 v[10:11], v[140:141], v[10:11]
	v_pk_mul_f32 v[12:13], v[148:149], v[12:13]
	v_pk_mul_f32 v[14:15], v[142:143], v[14:15]
	s_addc_u32 s53, s53, 0
	s_waitcnt lgkmcnt(0)
	v_pk_mul_f32 v[60:61], v[60:61], v[0:1]
	v_pk_mul_f32 v[62:63], v[62:63], v[2:3]
	ds_read_b128 v[0:3], v167 offset:128
	s_cmp_eq_u32 s52, 0x20000
	s_waitcnt lgkmcnt(0)
	v_pk_mul_f32 v[32:33], v[100:101], v[0:1]
	v_pk_mul_f32 v[34:35], v[96:97], v[2:3]
	ds_read_b128 v[0:3], v167 offset:160
	v_cvt_pk_bf16_f32 v100, v56, v57
	v_cvt_pk_bf16_f32 v101, v58, v59
	s_waitcnt lgkmcnt(0)
	v_pk_mul_f32 v[36:37], v[110:111], v[0:1]
	v_pk_mul_f32 v[38:39], v[102:103], v[2:3]
	ds_read_b128 v[0:3], v167 offset:192
	v_cvt_pk_bf16_f32 v102, v60, v61
	v_cvt_pk_bf16_f32 v103, v62, v63
	s_waitcnt lgkmcnt(0)
	v_pk_mul_f32 v[40:41], v[104:105], v[0:1]
	v_pk_mul_f32 v[42:43], v[98:99], v[2:3]
	ds_read_b128 v[0:3], v167 offset:224
	v_add_u32_e32 v104, 0x2000, v180
	s_waitcnt lgkmcnt(0)
	v_pk_mul_f32 v[44:45], v[116:117], v[0:1]
	v_pk_mul_f32 v[46:47], v[106:107], v[2:3]
	ds_read_b128 v[0:3], v167 offset:256
	s_waitcnt lgkmcnt(0)
	v_pk_mul_f32 v[16:17], v[122:123], v[0:1]
	v_pk_mul_f32 v[18:19], v[118:119], v[2:3]
	ds_read_b128 v[0:3], v167 offset:288
	s_waitcnt lgkmcnt(0)
	v_pk_mul_f32 v[20:21], v[130:131], v[0:1]
	v_pk_mul_f32 v[22:23], v[124:125], v[2:3]
	ds_read_b128 v[0:3], v167 offset:320
	s_waitcnt lgkmcnt(0)
	v_pk_mul_f32 v[24:25], v[126:127], v[0:1]
	v_pk_mul_f32 v[26:27], v[120:121], v[2:3]
	ds_read_b128 v[0:3], v167 offset:352
	s_waitcnt lgkmcnt(0)
	v_pk_mul_f32 v[28:29], v[132:133], v[0:1]
	v_pk_mul_f32 v[30:31], v[128:129], v[2:3]
	ds_read_b128 v[0:3], v167 offset:384
	ds_read2_b64 v[68:71], v180 offset1:2
	ds_read2_b64 v[96:99], v180 offset0:4 offset1:6
	s_waitcnt lgkmcnt(1)
	v_mfma_f32_32x32x16_bf16 v[80:95], v[64:67], v[68:71], 0
	ds_read2_b64 v[68:71], v104 offset0:64 offset1:66
	v_mul_f32_e64 v0, v136, v0
	v_mul_f32_e64 v1, v137, v1
	v_mul_f32_e64 v2, v134, v2
	v_mul_f32_e64 v3, v135, v3
	s_waitcnt lgkmcnt(0)
	v_mfma_f32_32x32x16_bf16 v[64:79], v[64:67], v[68:71], 0
	v_mfma_f32_32x32x16_bf16 v[80:95], v[100:103], v[96:99], v[80:95]
	ds_read2_b64 v[96:99], v104 offset0:68 offset1:70
	s_waitcnt lgkmcnt(0)
	v_mfma_f32_32x32x16_bf16 v[64:79], v[100:103], v[96:99], v[64:79]
	v_cvt_pk_bf16_f32 v96, v32, v33
	v_cvt_pk_bf16_f32 v97, v34, v35
	v_cvt_pk_bf16_f32 v98, v36, v37
	v_cvt_pk_bf16_f32 v99, v38, v39
	ds_read2_b64 v[100:103], v180 offset0:8 offset1:10
	s_waitcnt lgkmcnt(0)
	v_mfma_f32_32x32x16_bf16 v[80:95], v[96:99], v[100:103], v[80:95]
	ds_read2_b64 v[100:103], v104 offset0:72 offset1:74
	s_waitcnt lgkmcnt(0)
	v_mfma_f32_32x32x16_bf16 v[64:79], v[96:99], v[100:103], v[64:79]
	v_cvt_pk_bf16_f32 v96, v40, v41
	v_cvt_pk_bf16_f32 v97, v42, v43
	v_cvt_pk_bf16_f32 v98, v44, v45
	v_cvt_pk_bf16_f32 v99, v46, v47
	ds_read2_b64 v[100:103], v180 offset0:12 offset1:14
	s_waitcnt lgkmcnt(0)
	v_mfma_f32_32x32x16_bf16 v[80:95], v[96:99], v[100:103], v[80:95]
	ds_read2_b64 v[100:103], v104 offset0:76 offset1:78
	s_waitcnt lgkmcnt(0)
	v_mfma_f32_32x32x16_bf16 v[64:79], v[96:99], v[100:103], v[64:79]
	v_cvt_pk_bf16_f32 v96, v16, v17
	v_cvt_pk_bf16_f32 v97, v18, v19
	v_cvt_pk_bf16_f32 v98, v20, v21
	v_cvt_pk_bf16_f32 v99, v22, v23
	ds_read2_b64 v[100:103], v180 offset0:16 offset1:18
	s_waitcnt lgkmcnt(0)
	v_mfma_f32_32x32x16_bf16 v[80:95], v[96:99], v[100:103], v[80:95]
	ds_read2_b64 v[100:103], v104 offset0:80 offset1:82
	s_waitcnt lgkmcnt(0)
	v_mfma_f32_32x32x16_bf16 v[64:79], v[96:99], v[100:103], v[64:79]
	v_cvt_pk_bf16_f32 v96, v24, v25
	v_cvt_pk_bf16_f32 v97, v26, v27
	v_cvt_pk_bf16_f32 v98, v28, v29
	v_cvt_pk_bf16_f32 v99, v30, v31
	ds_read2_b64 v[100:103], v180 offset0:20 offset1:22
	s_waitcnt lgkmcnt(0)
	v_mfma_f32_32x32x16_bf16 v[80:95], v[96:99], v[100:103], v[80:95]
	ds_read2_b64 v[100:103], v104 offset0:84 offset1:86
	s_waitcnt lgkmcnt(0)
	v_mfma_f32_32x32x16_bf16 v[64:79], v[96:99], v[100:103], v[64:79]
	v_cvt_pk_bf16_f32 v96, v0, v1
	v_cvt_pk_bf16_f32 v97, v2, v3
	v_cvt_pk_bf16_f32 v98, v4, v5
	v_cvt_pk_bf16_f32 v99, v6, v7
	ds_read2_b64 v[100:103], v180 offset0:24 offset1:26
	s_waitcnt lgkmcnt(0)
	v_mfma_f32_32x32x16_bf16 v[80:95], v[96:99], v[100:103], v[80:95]
	ds_read2_b64 v[100:103], v104 offset0:88 offset1:90
	s_waitcnt lgkmcnt(0)
	v_mfma_f32_32x32x16_bf16 v[64:79], v[96:99], v[100:103], v[64:79]
	v_cvt_pk_bf16_f32 v96, v8, v9
	v_cvt_pk_bf16_f32 v97, v10, v11
	v_cvt_pk_bf16_f32 v98, v12, v13
	v_cvt_pk_bf16_f32 v99, v14, v15
	ds_read2_b64 v[100:103], v180 offset0:28 offset1:30
	s_waitcnt lgkmcnt(0)
	v_mfma_f32_32x32x16_bf16 v[80:95], v[96:99], v[100:103], v[80:95]
	ds_read2_b64 v[100:103], v104 offset0:92 offset1:94
	s_waitcnt lgkmcnt(0)
	v_mfma_f32_32x32x16_bf16 v[64:79], v[96:99], v[100:103], v[64:79]
	ds_read_b128 v[114:117], v157 offset:17408
	ds_read_b128 v[96:99], v157
	ds_read_b128 v[118:121], v157 offset:32
	ds_read_b128 v[122:125], v157 offset:17440
	s_waitcnt lgkmcnt(2)
	v_mfma_f32_32x32x16_bf16 v[96:111], v[114:117], v[96:99], 0
	s_waitcnt lgkmcnt(0)
	v_mfma_f32_32x32x16_bf16 v[96:111], v[122:125], v[118:121], v[96:111]
	ds_read_b128 v[118:121], v157 offset:17472
	ds_read_b128 v[126:129], v157 offset:64
	s_waitcnt lgkmcnt(0)
	v_mfma_f32_32x32x16_bf16 v[96:111], v[118:121], v[126:129], v[96:111]
	ds_read_b128 v[126:129], v157 offset:17504
	ds_read_b128 v[130:133], v157 offset:96
	s_waitcnt lgkmcnt(0)
	v_mfma_f32_32x32x16_bf16 v[96:111], v[126:129], v[130:133], v[96:111]
	ds_read_b128 v[130:133], v157 offset:17536
	ds_read_b128 v[134:137], v157 offset:128
	s_waitcnt lgkmcnt(0)
	v_mfma_f32_32x32x16_bf16 v[96:111], v[130:133], v[134:137], v[96:111]
	ds_read_b128 v[134:137], v157 offset:17568
	ds_read_b128 v[138:141], v157 offset:160
	s_waitcnt lgkmcnt(0)
	v_mfma_f32_32x32x16_bf16 v[96:111], v[134:137], v[138:141], v[96:111]
	ds_read_b128 v[138:141], v157 offset:17600
	ds_read_b128 v[142:145], v157 offset:192
	s_waitcnt lgkmcnt(0)
	v_mfma_f32_32x32x16_bf16 v[96:111], v[138:141], v[142:145], v[96:111]
	ds_read_b128 v[142:145], v157 offset:17632
	ds_read_b128 v[146:149], v157 offset:224
	s_waitcnt lgkmcnt(0)
	v_mfma_f32_32x32x16_bf16 v[96:111], v[142:145], v[146:149], v[96:111]
	s_nop 11
	v_cndmask_b32_e64 v146, v96, 0, s[34:35]
	v_cndmask_b32_e64 v96, v146, v96, s[30:31]
	v_cndmask_b32_e64 v97, 0, v97, s[30:31]
	v_cndmask_b32_e64 v98, v98, 0, s[28:29]
	v_cndmask_b32_e64 v99, v99, 0, s[26:27]
	v_cndmask_b32_e64 v100, v100, 0, s[24:25]
	v_cndmask_b32_e64 v101, v101, 0, s[22:23]
	v_cvt_pk_bf16_f32 v96, v96, v97
	v_cvt_pk_bf16_f32 v97, v98, v99
	v_cvt_pk_bf16_f32 v98, v100, v101
	v_add_u32_e32 v100, v171, v168
	v_add_u32_e32 v183, 0xd000, v100
	ds_read2_b64 v[146:149], v183 offset1:2
	ds_read2_b64 v[184:187], v183 offset0:4 offset1:6
	v_cndmask_b32_e64 v102, v102, 0, s[20:21]
	v_cndmask_b32_e64 v103, v103, 0, s[18:19]
	v_cvt_pk_bf16_f32 v99, v102, v103
	ds_read_b128 v[188:191], v157 offset:8704
	v_cndmask_b32_e64 v104, v104, 0, s[16:17]
	s_waitcnt lgkmcnt(2)
	v_mfma_f32_32x32x16_bf16 v[80:95], v[146:149], v[96:99], v[80:95]
	v_cndmask_b32_e64 v105, v105, 0, s[14:15]
	v_cndmask_b32_e64 v106, v106, 0, s[12:13]
	v_cndmask_b32_e64 v107, v107, 0, s[10:11]
	v_cndmask_b32_e64 v108, v108, 0, s[8:9]
	v_cndmask_b32_e64 v109, v109, 0, s[6:7]
	v_cndmask_b32_e64 v110, v110, 0, s[4:5]
	v_cndmask_b32_e64 v111, v111, 0, s[2:3]
	v_cvt_pk_bf16_f32 v96, v104, v105
	v_cvt_pk_bf16_f32 v97, v106, v107
	v_cvt_pk_bf16_f32 v98, v108, v109
	v_cvt_pk_bf16_f32 v99, v110, v111
	s_waitcnt lgkmcnt(1)
	s_nop 0
	v_mfma_f32_32x32x16_bf16 v[80:95], v[184:187], v[96:99], v[80:95]
	s_waitcnt lgkmcnt(0)
	v_mfma_f32_32x32x16_bf16 v[96:111], v[114:117], v[188:191], 0
	ds_read_b128 v[114:117], v157 offset:8736
	s_waitcnt lgkmcnt(0)
	v_mfma_f32_32x32x16_bf16 v[96:111], v[122:125], v[114:117], v[96:111]
	ds_read_b128 v[122:125], v157 offset:8768
	s_waitcnt lgkmcnt(0)
	v_mfma_f32_32x32x16_bf16 v[96:111], v[118:121], v[122:125], v[96:111]
	ds_read_b128 v[118:121], v157 offset:8800
	s_waitcnt lgkmcnt(0)
	v_mfma_f32_32x32x16_bf16 v[96:111], v[126:129], v[118:121], v[96:111]
	ds_read_b128 v[126:129], v157 offset:8832
	s_waitcnt lgkmcnt(0)
	v_mfma_f32_32x32x16_bf16 v[96:111], v[130:133], v[126:129], v[96:111]
	ds_read_b128 v[130:133], v157 offset:8864
	s_waitcnt lgkmcnt(0)
	v_mfma_f32_32x32x16_bf16 v[96:111], v[134:137], v[130:133], v[96:111]
	ds_read_b128 v[134:137], v157 offset:8896
	s_waitcnt lgkmcnt(0)
	v_mfma_f32_32x32x16_bf16 v[96:111], v[138:141], v[134:137], v[96:111]
	ds_read_b128 v[138:141], v157 offset:8928
	s_waitcnt lgkmcnt(0)
	v_mfma_f32_32x32x16_bf16 v[96:111], v[142:145], v[138:141], v[96:111]
	ds_read_b128 v[142:145], v157 offset:26144
	s_nop 10
	v_cvt_pk_bf16_f32 v96, v96, v97
	v_cvt_pk_bf16_f32 v97, v98, v99
	v_cvt_pk_bf16_f32 v98, v100, v101
	v_cvt_pk_bf16_f32 v99, v102, v103
	s_nop 1
	v_mfma_f32_32x32x16_bf16 v[64:79], v[146:149], v[96:99], v[64:79]
	v_cvt_pk_bf16_f32 v96, v104, v105
	v_cvt_pk_bf16_f32 v97, v106, v107
	v_cvt_pk_bf16_f32 v98, v108, v109
	v_cvt_pk_bf16_f32 v99, v110, v111
	s_nop 1
	v_mfma_f32_32x32x16_bf16 v[64:79], v[184:187], v[96:99], v[64:79]
	ds_read_b128 v[96:99], v157 offset:26112
	s_waitcnt lgkmcnt(0)
	v_mfma_f32_32x32x16_bf16 v[96:111], v[96:99], v[188:191], 0
	v_mfma_f32_32x32x16_bf16 v[96:111], v[142:145], v[114:117], v[96:111]
	ds_read_b128 v[114:117], v157 offset:26176
	s_waitcnt lgkmcnt(0)
	v_mfma_f32_32x32x16_bf16 v[96:111], v[114:117], v[122:125], v[96:111]
	ds_read_b128 v[114:117], v157 offset:26208
	s_waitcnt lgkmcnt(0)
	v_mfma_f32_32x32x16_bf16 v[96:111], v[114:117], v[118:121], v[96:111]
	ds_read_b128 v[114:117], v157 offset:26240
	s_waitcnt lgkmcnt(0)
	v_mfma_f32_32x32x16_bf16 v[96:111], v[114:117], v[126:129], v[96:111]
	ds_read_b128 v[114:117], v157 offset:26272
	s_waitcnt lgkmcnt(0)
	v_mfma_f32_32x32x16_bf16 v[96:111], v[114:117], v[130:133], v[96:111]
	ds_read_b128 v[114:117], v157 offset:26304
	s_waitcnt lgkmcnt(0)
	v_mfma_f32_32x32x16_bf16 v[96:111], v[114:117], v[134:137], v[96:111]
	ds_read_b128 v[114:117], v157 offset:26336
	v_ashrrev_i32_e32 v157, 31, v156
	s_waitcnt lgkmcnt(0)
	v_mfma_f32_32x32x16_bf16 v[96:111], v[114:117], v[138:141], v[96:111]
	s_nop 11
	v_cndmask_b32_e64 v114, v96, 0, s[34:35]
	v_cndmask_b32_e64 v96, v114, v96, s[30:31]
	v_cndmask_b32_e64 v97, 0, v97, s[30:31]
	v_cndmask_b32_e64 v98, v98, 0, s[28:29]
	v_cndmask_b32_e64 v99, v99, 0, s[26:27]
	v_cndmask_b32_e64 v100, v100, 0, s[24:25]
	v_cndmask_b32_e64 v101, v101, 0, s[22:23]
	v_cndmask_b32_e64 v102, v102, 0, s[20:21]
	v_cndmask_b32_e64 v103, v103, 0, s[18:19]
	v_cvt_pk_bf16_f32 v96, v96, v97
	v_cvt_pk_bf16_f32 v97, v98, v99
	v_cvt_pk_bf16_f32 v98, v100, v101
	v_cvt_pk_bf16_f32 v99, v102, v103
	ds_read2_b64 v[100:103], v183 offset0:8 offset1:10
	v_cndmask_b32_e64 v104, v104, 0, s[16:17]
	s_waitcnt lgkmcnt(0)
	v_mfma_f32_32x32x16_bf16 v[64:79], v[100:103], v[96:99], v[64:79]
	ds_read2_b64 v[100:103], v183 offset0:12 offset1:14
	v_cndmask_b32_e64 v105, v105, 0, s[14:15]
	v_cndmask_b32_e64 v106, v106, 0, s[12:13]
	v_cndmask_b32_e64 v107, v107, 0, s[10:11]
	v_cndmask_b32_e64 v108, v108, 0, s[8:9]
	v_cndmask_b32_e64 v109, v109, 0, s[6:7]
	v_cndmask_b32_e64 v110, v110, 0, s[4:5]
	v_cndmask_b32_e64 v111, v111, 0, s[2:3]
	v_cvt_pk_bf16_f32 v96, v104, v105
	v_cvt_pk_bf16_f32 v97, v106, v107
	v_cvt_pk_bf16_f32 v98, v108, v109
	v_cvt_pk_bf16_f32 v99, v110, v111
	v_add_u32_e32 v108, v171, v169
	s_waitcnt lgkmcnt(0)
	v_mfma_f32_32x32x16_bf16 v[64:79], v[100:103], v[96:99], v[64:79]
	ds_read_b128 v[96:99], v108 offset:53248
	ds_read_b128 v[100:103], v108 offset:53280
	ds_read_b128 v[104:107], v108 offset:53312
	ds_read_b128 v[108:111], v108 offset:53344
	ds_read_b128 v[114:117], v181 offset:34816
	ds_read_b128 v[118:121], v181 offset:34848
	s_waitcnt lgkmcnt(1)
	v_mfma_f32_32x32x16_bf16 v[48:63], v[114:117], v[96:99], v[48:63]
	ds_read_b128 v[114:117], v181 offset:34880
	s_waitcnt lgkmcnt(1)
	v_mfma_f32_32x32x16_bf16 v[48:63], v[118:121], v[100:103], v[48:63]
	s_waitcnt lgkmcnt(0)
	v_mfma_f32_32x32x16_bf16 v[48:63], v[114:117], v[104:107], v[48:63]
	ds_read_b128 v[114:117], v181 offset:34912
	s_waitcnt lgkmcnt(0)
	v_mfma_f32_32x32x16_bf16 v[48:63], v[114:117], v[108:111], v[48:63]
	ds_read_b128 v[114:117], v181 offset:39424
	s_waitcnt lgkmcnt(0)
	v_mfma_f32_32x32x16_bf16 v[32:47], v[114:117], v[96:99], v[32:47]
	ds_read_b128 v[114:117], v181 offset:39456
	s_waitcnt lgkmcnt(0)
	v_mfma_f32_32x32x16_bf16 v[32:47], v[114:117], v[100:103], v[32:47]
	ds_read_b128 v[114:117], v181 offset:39488
	s_waitcnt lgkmcnt(0)
	v_mfma_f32_32x32x16_bf16 v[32:47], v[114:117], v[104:107], v[32:47]
	ds_read_b128 v[114:117], v181 offset:39520
	s_waitcnt lgkmcnt(0)
	v_mfma_f32_32x32x16_bf16 v[32:47], v[114:117], v[108:111], v[32:47]
	ds_read_b128 v[114:117], v181 offset:44032
	s_waitcnt lgkmcnt(0)
	v_mfma_f32_32x32x16_bf16 v[16:31], v[114:117], v[96:99], v[16:31]
	ds_read_b128 v[114:117], v181 offset:44064
	s_waitcnt lgkmcnt(0)
	v_mfma_f32_32x32x16_bf16 v[16:31], v[114:117], v[100:103], v[16:31]
	ds_read_b128 v[114:117], v181 offset:44096
	s_waitcnt lgkmcnt(0)
	v_mfma_f32_32x32x16_bf16 v[16:31], v[114:117], v[104:107], v[16:31]
	ds_read_b128 v[114:117], v181 offset:44128
	s_waitcnt lgkmcnt(0)
	v_mfma_f32_32x32x16_bf16 v[16:31], v[114:117], v[108:111], v[16:31]
	ds_read_b128 v[114:117], v181 offset:48640
	s_waitcnt lgkmcnt(0)
	v_mfma_f32_32x32x16_bf16 v[0:15], v[114:117], v[96:99], v[0:15]
	ds_read_b128 v[96:99], v181 offset:48672
	s_waitcnt lgkmcnt(0)
	v_mfma_f32_32x32x16_bf16 v[0:15], v[96:99], v[100:103], v[0:15]
	ds_read_b128 v[96:99], v181 offset:48704
	s_waitcnt lgkmcnt(0)
	v_mfma_f32_32x32x16_bf16 v[0:15], v[96:99], v[104:107], v[0:15]
	ds_read_b128 v[96:99], v181 offset:48736
	s_waitcnt lgkmcnt(0)
	v_mfma_f32_32x32x16_bf16 v[0:15], v[96:99], v[108:111], v[0:15]
	ds_read_b128 v[96:99], v172
	ds_read_b128 v[100:103], v172 offset:32
	s_waitcnt lgkmcnt(1)
	v_mul_f32_e64 v108, v48, v96
	v_mul_f32_e64 v109, v49, v97
	v_pk_mul_f32 v[114:115], v[50:51], v[98:99]
	ds_read_b128 v[48:51], v172 offset:64
	s_waitcnt lgkmcnt(1)
	v_pk_mul_f32 v[52:53], v[52:53], v[100:101]
	v_pk_mul_f32 v[54:55], v[54:55], v[102:103]
	s_waitcnt lgkmcnt(0)
	v_pk_mul_f32 v[56:57], v[56:57], v[48:49]
	v_pk_mul_f32 v[58:59], v[58:59], v[50:51]
	ds_read_b128 v[48:51], v172 offset:96
	s_waitcnt lgkmcnt(0)
	v_pk_mul_f32 v[60:61], v[60:61], v[48:49]
	v_pk_mul_f32 v[62:63], v[62:63], v[50:51]
	ds_read_b128 v[48:51], v172 offset:128
	s_waitcnt lgkmcnt(0)
	v_pk_mul_f32 v[100:101], v[32:33], v[48:49]
	v_pk_mul_f32 v[96:97], v[34:35], v[50:51]
	ds_read_b128 v[32:35], v172 offset:160
	s_waitcnt lgkmcnt(0)
	v_pk_mul_f32 v[110:111], v[36:37], v[32:33]
	v_pk_mul_f32 v[102:103], v[38:39], v[34:35]
	ds_read_b128 v[32:35], v172 offset:192
	s_waitcnt lgkmcnt(0)
	v_pk_mul_f32 v[104:105], v[40:41], v[32:33]
	v_pk_mul_f32 v[98:99], v[42:43], v[34:35]
	ds_read_b128 v[32:35], v172 offset:224
	s_waitcnt lgkmcnt(0)
	v_pk_mul_f32 v[116:117], v[44:45], v[32:33]
	v_pk_mul_f32 v[106:107], v[46:47], v[34:35]
	ds_read_b128 v[32:35], v172 offset:256
	s_waitcnt lgkmcnt(0)
	v_pk_mul_f32 v[122:123], v[16:17], v[32:33]
	v_pk_mul_f32 v[118:119], v[18:19], v[34:35]
	ds_read_b128 v[16:19], v172 offset:288
	s_waitcnt lgkmcnt(0)
	v_pk_mul_f32 v[130:131], v[20:21], v[16:17]
	v_pk_mul_f32 v[124:125], v[22:23], v[18:19]
	ds_read_b128 v[16:19], v172 offset:320
	s_waitcnt lgkmcnt(0)
	v_pk_mul_f32 v[126:127], v[24:25], v[16:17]
	v_pk_mul_f32 v[120:121], v[26:27], v[18:19]
	ds_read_b128 v[16:19], v172 offset:352
	s_waitcnt lgkmcnt(0)
	v_pk_mul_f32 v[132:133], v[28:29], v[16:17]
	v_pk_mul_f32 v[128:129], v[30:31], v[18:19]
	ds_read_b128 v[16:19], v172 offset:384
	v_lshlrev_b64 v[30:31], 12, v[156:157]
	s_waitcnt lgkmcnt(0)
	v_pk_mul_f32 v[136:137], v[0:1], v[16:17]
	v_pk_mul_f32 v[134:135], v[2:3], v[18:19]
	ds_read_b128 v[0:3], v172 offset:416
	s_waitcnt lgkmcnt(0)
	v_pk_mul_f32 v[144:145], v[4:5], v[0:1]
	v_pk_mul_f32 v[138:139], v[6:7], v[2:3]
	ds_read_b128 v[0:3], v172 offset:448
	s_waitcnt lgkmcnt(0)
	v_pk_mul_f32 v[146:147], v[8:9], v[0:1]
	v_pk_mul_f32 v[140:141], v[10:11], v[2:3]
	ds_read_b128 v[0:3], v172 offset:480
	s_waitcnt lgkmcnt(0)
	s_barrier
	ds_write_b128 v182, v[80:83]
	ds_write_b128 v182, v[84:87] offset:32
	ds_write_b128 v182, v[88:91] offset:64
	ds_write_b128 v182, v[92:95] offset:96
	ds_write_b128 v182, v[64:67] offset:16896
	ds_write_b128 v182, v[68:71] offset:16928
	ds_write_b128 v182, v[72:75] offset:16960
	ds_write_b128 v182, v[76:79] offset:16992
	v_pk_mul_f32 v[148:149], v[12:13], v[0:1]
	v_pk_mul_f32 v[142:143], v[14:15], v[2:3]
	s_waitcnt lgkmcnt(0)
	s_barrier
	ds_read_b128 v[16:19], v173 offset:256
	ds_read_b128 v[12:15], v173 offset:272
	v_lshl_add_u64 v[64:65], v[152:153], 0, v[30:31]
	s_waitcnt lgkmcnt(1)
	v_pk_mul_f32 v[4:5], v[16:17], v[16:17]
	s_waitcnt lgkmcnt(0)
	v_pk_mul_f32 v[6:7], v[12:13], v[12:13]
	v_pk_mul_f32 v[0:1], v[18:19], v[18:19]
	v_pk_mul_f32 v[2:3], v[14:15], v[14:15]
	v_mov_b32_e32 v8, v4
	v_mov_b32_e32 v9, v6
	v_mov_b32_e32 v6, v5
	v_pk_add_f32 v[4:5], v[8:9], v[6:7]
	v_mov_b32_e32 v6, v0
	v_mov_b32_e32 v7, v2
	v_pk_add_f32 v[4:5], v[4:5], v[6:7]
	v_mov_b32_e32 v2, v1
	v_pk_add_f32 v[66:67], v[4:5], v[2:3]
	ds_read_b128 v[4:7], v173 offset:384
	ds_read_b128 v[0:3], v173 offset:400
	s_waitcnt lgkmcnt(1)
	v_pk_mul_f32 v[20:21], v[4:5], v[4:5]
	s_waitcnt lgkmcnt(0)
	v_pk_mul_f32 v[22:23], v[0:1], v[0:1]
	v_pk_mul_f32 v[8:9], v[6:7], v[6:7]
	v_pk_mul_f32 v[10:11], v[2:3], v[2:3]
	v_mov_b32_e32 v24, v20
	v_mov_b32_e32 v25, v22
	v_mov_b32_e32 v22, v21
	v_pk_add_f32 v[20:21], v[24:25], v[22:23]
	v_mov_b32_e32 v22, v8
	v_mov_b32_e32 v23, v10
	v_mov_b32_e32 v10, v9
	v_lshl_add_u64 v[8:9], v[156:157], 0, s[46:47]
	v_lshlrev_b64 v[8:9], 8, v[8:9]
	v_pk_add_f32 v[20:21], v[20:21], v[22:23]
	v_lshl_add_u64 v[28:29], v[150:151], 0, v[8:9]
	v_pk_add_f32 v[68:69], v[20:21], v[10:11]
	ds_read_b128 v[48:51], v173
	ds_read_b128 v[40:43], v173 offset:16
	ds_read_b128 v[32:35], v173 offset:128
	ds_read_b128 v[28:31], v173 offset:144
	global_load_dwordx4 v[36:39], v[154:155], off offset:16
	global_load_dwordx4 v[44:47], v[154:155], off
	s_waitcnt lgkmcnt(3)
	v_mov_b32_e32 v84, v49
	s_waitcnt lgkmcnt(2)
	v_mov_b32_e32 v85, v41
	v_mov_b32_e32 v78, v48
	v_mov_b32_e32 v79, v40
	v_pk_mul_f32 v[84:85], v[84:85], v[84:85]
	s_waitcnt lgkmcnt(1)
	v_mov_b32_e32 v90, v33
	v_pk_fma_f32 v[78:79], v[78:79], v[78:79], v[84:85]
	s_waitcnt lgkmcnt(0)
	v_mov_b32_e32 v91, v29
	v_mov_b32_e32 v74, v51
	v_mov_b32_e32 v75, v43
	v_mov_b32_e32 v88, v32
	v_mov_b32_e32 v89, v28
	v_pk_mul_f32 v[90:91], v[90:91], v[90:91]
	v_mov_b32_e32 v86, v35
	v_pk_fma_f32 v[88:89], v[88:89], v[88:89], v[90:91]
	v_mov_b32_e32 v87, v31
	v_add_u32_e32 v156, 64, v156
	s_waitcnt vmcnt(2)
	v_lshlrev_b32_e32 v80, 16, v229
	v_and_b32_e32 v81, 0xffff0000, v229
	v_lshlrev_b32_e32 v82, 16, v228
	v_and_b32_e32 v83, 0xffff0000, v228
	v_mov_b32_e32 v70, v50
	v_mov_b32_e32 v71, v42
	v_pk_fma_f32 v[70:71], v[70:71], v[70:71], v[78:79]
	v_lshlrev_b32_e32 v76, 16, v230
	v_and_b32_e32 v77, 0xffff0000, v230
	v_pk_fma_f32 v[84:85], v[74:75], v[74:75], v[70:71]
	v_lshlrev_b32_e32 v78, 16, v231
	v_and_b32_e32 v79, 0xffff0000, v231
	v_lshlrev_b32_e32 v72, 16, v225
	v_and_b32_e32 v73, 0xffff0000, v225
	v_lshlrev_b32_e32 v74, 16, v224
	v_and_b32_e32 v75, 0xffff0000, v224
	v_mov_b32_e32 v24, v34
	v_mov_b32_e32 v25, v30
	v_pk_fma_f32 v[24:25], v[24:25], v[24:25], v[88:89]
	v_lshlrev_b32_e32 v70, 16, v226
	v_and_b32_e32 v71, 0xffff0000, v226
	v_pk_fma_f32 v[24:25], v[86:87], v[86:87], v[24:25]
	v_add_f32_e32 v26, v84, v85
	v_add_f32_e32 v24, v26, v24
	v_add_f32_e32 v24, v24, v25
	v_add_f32_e32 v24, v24, v66
	v_add_f32_e32 v24, v24, v67
	v_add_f32_e32 v24, v24, v68
	v_add_f32_e32 v24, v24, v69
	ds_bpermute_b32 v25, v174, v24
	v_lshlrev_b32_e32 v26, 16, v227
	v_and_b32_e32 v27, 0xffff0000, v227
	s_waitcnt lgkmcnt(0)
	v_add_f32_e32 v24, v24, v25
	ds_bpermute_b32 v25, v175, v24
	s_waitcnt lgkmcnt(0)
	v_add_f32_e32 v24, v24, v25
	v_fmamk_f32 v24, v24, 0x3c000000, v161
	v_cmp_gt_f32_e64 s[36:37], s70, v24
	v_mul_f32_e32 v25, 0x4b800000, v24
	s_nop 0
	v_cndmask_b32_e64 v24, v24, v25, s[36:37]
	v_rsq_f32_e32 v24, v24
	s_nop 0
	v_mul_f32_e32 v25, 0x45800000, v24
	v_cndmask_b32_e64 v24, v24, v25, s[36:37]
	v_pk_mul_f32 v[48:49], v[48:49], v[24:25] op_sel_hi:[1,0]
	v_pk_mul_f32 v[40:41], v[40:41], v[24:25] op_sel_hi:[1,0]
	s_waitcnt vmcnt(0)
	v_pk_mul_f32 v[44:45], v[44:45], v[48:49]
	v_pk_mul_f32 v[48:49], v[50:51], v[24:25] op_sel_hi:[1,0]
	v_pk_mul_f32 v[36:37], v[36:37], v[40:41]
	v_pk_mul_f32 v[46:47], v[46:47], v[48:49]
	v_pk_mul_f32 v[44:45], v[44:45], v[82:83]
	v_pk_mul_f32 v[46:47], v[46:47], v[80:81]
	v_pk_mul_f32 v[36:37], v[36:37], v[76:77]
	v_cvt_pk_bf16_f32 v44, v44, v45
	v_cvt_pk_bf16_f32 v45, v46, v47
	v_cvt_pk_bf16_f32 v46, v36, v37
	v_pk_mul_f32 v[36:37], v[42:43], v[24:25] op_sel_hi:[1,0]
	v_pk_mul_f32 v[32:33], v[32:33], v[24:25] op_sel_hi:[1,0]
	v_pk_mul_f32 v[36:37], v[36:37], v[38:39]
	v_pk_mul_f32 v[34:35], v[34:35], v[24:25] op_sel_hi:[1,0]
	v_pk_mul_f32 v[36:37], v[36:37], v[78:79]
	v_pk_mul_f32 v[28:29], v[28:29], v[24:25] op_sel_hi:[1,0]
	v_cvt_pk_bf16_f32 v47, v36, v37
	global_store_dwordx4 v[64:65], v[44:47], off
	global_load_dwordx4 v[36:39], v[154:155], off offset:144
	global_load_dwordx4 v[40:43], v[154:155], off offset:128
	v_pk_mul_f32 v[16:17], v[16:17], v[24:25] op_sel_hi:[1,0]
	v_pk_mul_f32 v[18:19], v[18:19], v[24:25] op_sel_hi:[1,0]
	v_pk_mul_f32 v[12:13], v[12:13], v[24:25] op_sel_hi:[1,0]
	v_pk_mul_f32 v[4:5], v[4:5], v[24:25] op_sel_hi:[1,0]
	v_pk_mul_f32 v[6:7], v[6:7], v[24:25] op_sel_hi:[1,0]
	v_pk_mul_f32 v[0:1], v[0:1], v[24:25] op_sel_hi:[1,0]
	s_waitcnt vmcnt(1)
	v_pk_mul_f32 v[28:29], v[28:29], v[36:37]
	s_waitcnt vmcnt(0)
	v_pk_mul_f32 v[32:33], v[32:33], v[40:41]
	v_pk_mul_f32 v[34:35], v[34:35], v[42:43]
	v_pk_mul_f32 v[32:33], v[32:33], v[74:75]
	v_pk_mul_f32 v[34:35], v[34:35], v[72:73]
	v_pk_mul_f32 v[28:29], v[28:29], v[70:71]
	v_cvt_pk_bf16_f32 v32, v32, v33
	v_cvt_pk_bf16_f32 v33, v34, v35
	v_cvt_pk_bf16_f32 v34, v28, v29
	v_pk_mul_f32 v[28:29], v[30:31], v[24:25] op_sel_hi:[1,0]
	s_nop 0
	v_pk_mul_f32 v[28:29], v[28:29], v[38:39]
	s_nop 0
	v_pk_mul_f32 v[26:27], v[28:29], v[26:27]
	s_nop 0
	v_cvt_pk_bf16_f32 v35, v26, v27
	global_store_dwordx4 v[64:65], v[32:35], off offset:64
	global_load_dwordx4 v[26:29], v[154:155], off offset:272
	s_nop 0
	global_load_dwordx4 v[30:33], v[154:155], off offset:256
	s_waitcnt vmcnt(1)
	v_pk_mul_f32 v[12:13], v[12:13], v[26:27]
	s_waitcnt vmcnt(0)
	v_pk_mul_f32 v[16:17], v[16:17], v[30:31]
	v_lshlrev_b32_e32 v30, 16, v220
	v_and_b32_e32 v31, 0xffff0000, v220
	v_pk_mul_f32 v[18:19], v[18:19], v[32:33]
	v_lshlrev_b32_e32 v20, 16, v221
	v_and_b32_e32 v21, 0xffff0000, v221
	v_pk_mul_f32 v[16:17], v[16:17], v[30:31]
	v_pk_mul_f32 v[18:19], v[18:19], v[20:21]
	v_cvt_pk_bf16_f32 v16, v16, v17
	v_cvt_pk_bf16_f32 v17, v18, v19
	v_lshlrev_b32_e32 v18, 16, v222
	v_and_b32_e32 v19, 0xffff0000, v222
	v_pk_mul_f32 v[12:13], v[12:13], v[18:19]
	s_nop 0
	v_cvt_pk_bf16_f32 v18, v12, v13
	v_pk_mul_f32 v[12:13], v[14:15], v[24:25] op_sel_hi:[1,0]
	v_lshlrev_b32_e32 v14, 16, v223
	v_pk_mul_f32 v[12:13], v[12:13], v[28:29]
	v_and_b32_e32 v15, 0xffff0000, v223
	v_pk_mul_f32 v[12:13], v[12:13], v[14:15]
	s_nop 0
	v_cvt_pk_bf16_f32 v19, v12, v13
	global_store_dwordx4 v[64:65], v[16:19], off offset:128
	global_load_dwordx4 v[12:15], v[154:155], off offset:400
	s_nop 0
	global_load_dwordx4 v[16:19], v[154:155], off offset:384
	s_waitcnt vmcnt(1)
	v_pk_mul_f32 v[0:1], v[0:1], v[12:13]
	s_waitcnt vmcnt(0)
	v_pk_mul_f32 v[4:5], v[4:5], v[16:17]
	v_lshlrev_b32_e32 v16, 16, v216
	v_and_b32_e32 v17, 0xffff0000, v216
	v_pk_mul_f32 v[6:7], v[6:7], v[18:19]
	v_lshlrev_b32_e32 v8, 16, v217
	v_and_b32_e32 v9, 0xffff0000, v217
	v_pk_mul_f32 v[4:5], v[4:5], v[16:17]
	v_pk_mul_f32 v[6:7], v[6:7], v[8:9]
	v_cvt_pk_bf16_f32 v4, v4, v5
	v_cvt_pk_bf16_f32 v5, v6, v7
	v_lshlrev_b32_e32 v6, 16, v218
	v_and_b32_e32 v7, 0xffff0000, v218
	v_pk_mul_f32 v[0:1], v[0:1], v[6:7]
	s_nop 0
	v_cvt_pk_bf16_f32 v6, v0, v1
	v_pk_mul_f32 v[0:1], v[2:3], v[24:25] op_sel_hi:[1,0]
	v_lshlrev_b32_e32 v2, 16, v219
	v_pk_mul_f32 v[0:1], v[0:1], v[14:15]
	v_and_b32_e32 v3, 0xffff0000, v219
	v_pk_mul_f32 v[0:1], v[0:1], v[2:3]
	s_nop 0
	v_cvt_pk_bf16_f32 v7, v0, v1
	global_store_dwordx4 v[64:65], v[4:7], off offset:192
	s_cbranch_scc1 .LBB0_425
